# latent Hyena K loop: A pointers kept in registers and advanced (2 VALU) instead of rebuilt from the counter (7 VALU), dead B pointer update removed
# speedup vs baseline: 1.0049x; 1.0049x over previous
; DI void hyena_item_lat(const Params& p, int l, int it) {
;     ...
;   const int c = it >> 2, f = l, L = 2048, posoff = CTXL;
;   const int tt0 = (it & 3) * 512 + w * 128;
;   const u16* R0 = WSP(const u16, OFF_RF) + ((size_t)(f * 256 + c) * 2) * RSTR;
;   const u16* R1 = R0 + RSTR;
;   const u16* UT = WSP(const u16, OFF_UT);
;   const int l16 = lane & 15, kg = lane >> 4;
;   f32x4 acc[8];
; #pragma unroll
;   for (int i = 0; i < 8; ++i) acc[i] = (f32x4){0.f, 0.f, 0.f, 0.f};
;   const u16* ub = UT + ((size_t)(c * 16 + l16)) * TPB + posoff + kg * 8;
;   const u16* rsel = (l16 & 1) ? (R1 - 1) : R0;
;   const int nb = L - (tt0 + l16) + kg * 8;
;   union AF { u32 u[4]; bf16x8 v; };
;   AF a[8];
;     ...
; #pragma unroll
;   for (int i = 2; i < 8; ++i) HY_LOADA(a[i], nb - 16 * i)
; #pragma unroll 1
;   for (int sb = 0; sb < L; sb += 128) {
; #pragma unroll
;     for (int u = 0; u < 4; ++u) {
;       const int s0 = sb + 32 * u;
;       HY_LOADA(a[(0 - 2 * u) & 7], nb + s0)
;       HY_LOADA(a[(1 - 2 * u) & 7], nb - 16 + s0)
;       const bf16x8 bfrag = *(const bf16x8*)(ub + s0);
; #pragma unroll
;       for (int i = 0; i < 8; ++i) acc[i] = __builtin_amdgcn_mfma_f32_16x16x32_bf16(a[(i - 2 * u) & 7].v, bfrag, acc[i], 0, 0, 0);
;     }
;   }
.LBB0_1137:
	s_andn2_b64 vcc, exec, s[34:35]
	s_cbranch_vccnz .LBB0_1141
	s_ashr_i32 s34, s13, 2
	v_mov_b32_e32 v0, v218
	v_mov_b32_e32 v1, v218
	s_add_i32 s36, s34, s42
	s_lshl_b32 s13, s13, 9
	s_ashr_i32 s37, s36, 31
	s_mul_i32 s38, s36, 0x4040
	v_readlane_b32 s16, v254, 47
	v_lshlrev_b32_e32 v1, 1, v1
	s_mul_hi_i32 s35, s36, 0x4040
	v_readlane_b32 s17, v254, 48
	s_add_u32 s38, s16, s38
	v_and_b32_e32 v1, 0xffffff80, v1
	s_addc_u32 s39, s17, s35
	s_and_b32 s13, s13, 0x600
	v_add_u32_e32 v63, s13, v1
	v_and_b32_e32 v62, 15, v0
	v_bfe_u32 v64, v0, 4, 2
	v_bfe_i32 v0, v0, 0, 1
	v_lshlrev_b32_e32 v1, 3, v64
	v_and_b32_e32 v172, 0x201e, v0
	v_or_b32_e32 v0, v63, v62
	v_sub_u32_e32 v58, v1, v0
	v_lshl_add_u64 v[56:57], s[38:39], 0, v[172:173]
	v_ashrrev_i32_e32 v59, 31, v58
	v_lshl_add_u64 v[0:1], v[58:59], 1, v[56:57]
	global_load_dwordx4 v[40:43], v[0:1], off offset:4032
	global_load_dwordx4 v[44:47], v[0:1], off offset:4000
	global_load_dwordx4 v[32:35], v[0:1], off offset:3968
	global_load_dwordx4 v[36:39], v[0:1], off offset:3936
	global_load_dwordx4 v[48:51], v[0:1], off offset:3904
	global_load_dwordx4 v[52:55], v[0:1], off offset:3872
	s_lshl_b32 s35, s34, 4
	v_or_b32_e32 v59, s35, v62
	v_mad_i64_i32 v[0:1], s[38:39], v59, s9, 0
	v_readlane_b32 s16, v255, 56
	v_lshl_or_b32 v0, v64, 4, v0
	v_readlane_b32 s17, v255, 57
	v_mov_b32_e32 v28, 0
	s_mov_b64 s[46:47], s[20:21]
	s_movk_i32 s13, 0xff80
	v_lshl_add_u64 v[60:61], s[16:17], 0, v[0:1]
	v_mov_b32_e32 v29, v28
	v_mov_b32_e32 v30, v28
	v_mov_b32_e32 v31, v28
	v_mov_b32_e32 v24, v28
	v_mov_b32_e32 v25, v28
	v_mov_b32_e32 v26, v28
	v_mov_b32_e32 v27, v28
	v_mov_b32_e32 v20, v28
	v_mov_b32_e32 v21, v28
	v_mov_b32_e32 v22, v28
	v_mov_b32_e32 v23, v28
	v_mov_b32_e32 v16, v28
	v_mov_b32_e32 v17, v28
	v_mov_b32_e32 v18, v28
	v_mov_b32_e32 v19, v28
	v_mov_b32_e32 v12, v28
	v_mov_b32_e32 v13, v28
	v_mov_b32_e32 v14, v28
	v_mov_b32_e32 v15, v28
	v_mov_b32_e32 v8, v28
	v_mov_b32_e32 v9, v28
	v_mov_b32_e32 v10, v28
	v_mov_b32_e32 v11, v28
	v_mov_b32_e32 v4, v28
	v_mov_b32_e32 v5, v28
	v_mov_b32_e32 v6, v28
	v_mov_b32_e32 v7, v28
	v_mov_b32_e32 v0, v28
	v_mov_b32_e32 v1, v28
	v_mov_b32_e32 v2, v28
	v_mov_b32_e32 v3, v28
	v_and_b32_e32 v92, 0xc0, v218
	v_mov_b32_e32 v93, 0
	v_lshlrev_b32_e32 v94, 4, v218
	v_and_b32_e32 v95, 63, v218
	v_lshl_add_u64 v[90:91], v[92:93], 0, v[60:61]
	v_lshlrev_b32_e32 v95, 4, v95
	global_load_dwordx4 v[82:85], v[90:91], off offset:-192
	v_add_u32_e32 v78, 0x800, v58
	v_add_u32_e32 v80, 0x7f0, v58
	v_ashrrev_i32_e32 v79, 31, v78
	v_ashrrev_i32_e32 v81, 31, v80
	v_lshl_add_u64 v[78:79], v[78:79], 1, v[56:57]
	v_lshl_add_u64 v[80:81], v[80:81], 1, v[56:57]
.LBB0_1139:
	s_waitcnt vmcnt(0)
	ds_write_b128 v94, v[82:85]
	s_waitcnt lgkmcnt(0)
	s_barrier
	ds_read_b128 v[66:69], v95
	ds_read_b128 v[70:73], v95 offset:1024
	ds_read_b128 v[86:89], v95 offset:2048
	ds_read_b128 v[74:77], v95 offset:3072
	v_xor_b32_e32 v94, 0x1000, v94
	v_xor_b32_e32 v95, 0x1000, v95
	s_mov_b64 s[38:39], 0x100
	s_waitcnt lgkmcnt(0)
	v_mfma_f32_16x16x32_bf16 v[4:7], v[48:51], v[66:69], v[4:7]
	v_mfma_f32_16x16x32_bf16 v[0:3], v[52:55], v[66:69], v[0:3]
	v_mfma_f32_16x16x32_bf16 v[12:15], v[32:35], v[66:69], v[12:15]
	global_load_dwordx4 v[48:51], v[78:79], off offset:64
	global_load_dwordx4 v[52:55], v[80:81], off offset:64
	s_addk_i32 s13, 0x80
	v_mfma_f32_16x16x32_bf16 v[8:11], v[36:39], v[66:69], v[8:11]
	s_cmpk_lt_u32 s13, 0x780
	v_mfma_f32_16x16x32_bf16 v[4:7], v[32:35], v[70:73], v[4:7]
	global_load_dwordx4 v[32:35], v[78:79], off
	v_mfma_f32_16x16x32_bf16 v[0:3], v[36:39], v[70:73], v[0:3]
	global_load_dwordx4 v[36:39], v[80:81], off
	v_mfma_f32_16x16x32_bf16 v[20:23], v[40:43], v[66:69], v[20:23]
	v_mfma_f32_16x16x32_bf16 v[16:19], v[44:47], v[66:69], v[16:19]
	s_waitcnt vmcnt(1)
	v_mfma_f32_16x16x32_bf16 v[28:31], v[32:35], v[66:69], v[28:31]
	s_waitcnt vmcnt(0)
	v_mfma_f32_16x16x32_bf16 v[24:27], v[36:39], v[66:69], v[24:27]
	global_load_dwordx4 v[82:85], v[90:91], off offset:64
	v_lshl_add_u64 v[90:91], v[90:91], 0, s[38:39]
	v_mfma_f32_16x16x32_bf16 v[12:15], v[40:43], v[70:73], v[12:15]
	v_mfma_f32_16x16x32_bf16 v[8:11], v[44:47], v[70:73], v[8:11]
	v_mfma_f32_16x16x32_bf16 v[20:23], v[32:35], v[70:73], v[20:23]
	v_mfma_f32_16x16x32_bf16 v[16:19], v[36:39], v[70:73], v[16:19]
	v_mfma_f32_16x16x32_bf16 v[28:31], v[48:51], v[70:73], v[28:31]
	v_mfma_f32_16x16x32_bf16 v[24:27], v[52:55], v[70:73], v[24:27]
	v_mfma_f32_16x16x32_bf16 v[4:7], v[40:43], v[86:89], v[4:7]
	global_load_dwordx4 v[40:43], v[78:79], off offset:192
	v_mfma_f32_16x16x32_bf16 v[0:3], v[44:47], v[86:89], v[0:3]
	global_load_dwordx4 v[44:47], v[80:81], off offset:192
	v_mfma_f32_16x16x32_bf16 v[12:15], v[32:35], v[86:89], v[12:15]
	v_mfma_f32_16x16x32_bf16 v[8:11], v[36:39], v[86:89], v[8:11]
	v_mfma_f32_16x16x32_bf16 v[4:7], v[32:35], v[74:77], v[4:7]
	global_load_dwordx4 v[32:35], v[78:79], off offset:128
	v_mfma_f32_16x16x32_bf16 v[0:3], v[36:39], v[74:77], v[0:3]
	global_load_dwordx4 v[36:39], v[80:81], off offset:128
	v_lshl_add_u64 v[78:79], v[78:79], 0, s[38:39]
	v_lshl_add_u64 v[80:81], v[80:81], 0, s[38:39]
	v_mfma_f32_16x16x32_bf16 v[20:23], v[48:51], v[86:89], v[20:23]
	v_mfma_f32_16x16x32_bf16 v[16:19], v[52:55], v[86:89], v[16:19]
	v_mfma_f32_16x16x32_bf16 v[12:15], v[48:51], v[74:77], v[12:15]
	v_mfma_f32_16x16x32_bf16 v[8:11], v[52:55], v[74:77], v[8:11]
	s_waitcnt vmcnt(1)
	v_mfma_f32_16x16x32_bf16 v[28:31], v[32:35], v[86:89], v[28:31]
	s_waitcnt vmcnt(0)
	v_mfma_f32_16x16x32_bf16 v[24:27], v[36:39], v[86:89], v[24:27]
	v_mfma_f32_16x16x32_bf16 v[20:23], v[32:35], v[74:77], v[20:23]
	v_mfma_f32_16x16x32_bf16 v[16:19], v[36:39], v[74:77], v[16:19]
	v_mfma_f32_16x16x32_bf16 v[28:31], v[40:43], v[74:77], v[28:31]
	v_mfma_f32_16x16x32_bf16 v[24:27], v[44:47], v[74:77], v[24:27]
	s_cbranch_scc1 .LBB0_1139
; DI float bf2f(u16 v) { return __uint_as_float(((u32)v) << 16); }
; DI void hyena_item_lat(const Params& p, int l, int it) {
;     ...
;   float ssq = 0.f;
;   for (int t = 0; t < 32; ++t) ssq += WSP(const float, OFF_PART)[(size_t)(f * 32 + t) * 256 + c];
;   const float scale = rsqrtf(ssq + EPSF);
;   const float bias = p.in[I_HYBIAS][l * 256 + c];
;   const u16* X1C = WSP(const u16, OFF_X1C);
;   u16* YM = WSP(u16, OFF_ACT);
;   const int b = l16;
; #pragma unroll
;   for (int i = 0; i < 8; ++i)
; #pragma unroll
;     for (int r = 0; r < 4; ++r) {
;       const int t = tt0 + 16 * i + kg * 4 + r;
;       const size_t row = (size_t)b * TPB + posoff + t;
;       const float uu = bf2f(UT[((size_t)(c * 16 + b)) * TPB + posoff + t]);
	s_waitcnt vmcnt(0)
	v_mov_b64_e32 v[32:33], s[96:97]
	v_mad_i64_i32 v[32:33], s[38:39], v59, s9, v[32:33]
	s_mov_b64 s[38:39], 0x15600200
	s_ashr_i32 s35, s34, 31
	v_lshl_add_u64 v[32:33], v[32:33], 0, s[38:39]
	s_lshl_b64 s[38:39], s[34:35], 2
	s_add_u32 s38, s43, s38
	s_addc_u32 s39, s44, s39
	global_load_dword v38, v173, s[38:39]
	global_load_dword v39, v173, s[38:39] offset:1024
	global_load_dword v40, v173, s[38:39] offset:2048
	global_load_dword v41, v173, s[38:39] offset:3072
	v_mov_b32_e32 v92, 0x1000
	global_load_dword v42, v92, s[38:39]
	global_load_dword v43, v92, s[38:39] offset:1024
	global_load_dword v44, v92, s[38:39] offset:2048
	global_load_dword v45, v92, s[38:39] offset:3072
	v_mov_b32_e32 v92, 0x2000
	global_load_dword v46, v92, s[38:39]
	global_load_dword v47, v92, s[38:39] offset:1024
	global_load_dword v48, v92, s[38:39] offset:2048
	global_load_dword v49, v92, s[38:39] offset:3072
	v_mov_b32_e32 v92, 0x3000
	global_load_dword v50, v92, s[38:39]
	global_load_dword v51, v92, s[38:39] offset:1024
	global_load_dword v52, v92, s[38:39] offset:2048
	global_load_dword v53, v92, s[38:39] offset:3072
	v_mov_b32_e32 v92, 0x4000
	global_load_dword v54, v92, s[38:39]
	global_load_dword v55, v92, s[38:39] offset:1024
	global_load_dword v56, v92, s[38:39] offset:2048
	global_load_dword v57, v92, s[38:39] offset:3072
	v_mov_b32_e32 v92, 0x5000
	global_load_dword v58, v92, s[38:39]
	global_load_dword v65, v92, s[38:39] offset:1024
	global_load_dword v66, v92, s[38:39] offset:2048
	global_load_dword v67, v92, s[38:39] offset:3072
	v_mov_b32_e32 v92, 0x6000
	global_load_dword v68, v92, s[38:39]
	global_load_dword v69, v92, s[38:39] offset:1024
	global_load_dword v70, v92, s[38:39] offset:2048
	global_load_dword v71, v92, s[38:39] offset:3072
	v_mov_b32_e32 v92, 0x7000
	global_load_dword v72, v92, s[38:39]
	global_load_dword v73, v92, s[38:39] offset:1024
	global_load_dword v74, v92, s[38:39] offset:2048
	global_load_dword v75, v92, s[38:39] offset:3072
	v_readlane_b32 s16, v254, 29
	s_lshl_b64 s[36:37], s[36:37], 2
	v_readlane_b32 s18, v254, 31
	v_readlane_b32 s19, v254, 32
	s_add_u32 s36, s18, s36
	s_addc_u32 s37, s19, s37
	global_load_dword v37, v173, s[36:37]
	s_movk_i32 s13, 0x900
	v_lshl_or_b32 v34, v64, 2, v63
	v_mov_b32_e32 v35, 0x100
	v_mad_u32_u24 v172, v62, s13, v35
	v_mov_b32_e32 v35, 0
	v_lshl_add_u64 v[94:95], v[34:35], 1, v[32:33]
	global_load_dwordx2 v[76:77], v[94:95], off
	global_load_dwordx2 v[78:79], v[94:95], off offset:32
	global_load_dwordx2 v[80:81], v[94:95], off offset:64
	global_load_dwordx2 v[82:83], v[94:95], off offset:96
	global_load_dwordx2 v[84:85], v[94:95], off offset:128
	global_load_dwordx2 v[86:87], v[94:95], off offset:160
	global_load_dwordx2 v[88:89], v[94:95], off offset:192
	global_load_dwordx2 v[90:91], v[94:95], off offset:224
	v_readlane_b32 s17, v254, 30
	s_lshl_b64 s[34:35], s[34:35], 1
	v_readlane_b32 s16, v255, 42
	v_readlane_b32 s17, v255, 43
	v_readlane_b32 s20, v254, 33
	v_readlane_b32 s21, v254, 34
	v_readlane_b32 s24, v254, 37
	v_readlane_b32 s18, v254, 10
	s_mov_b64 s[20:21], s[46:47]
	s_mov_b32 s24, s64
	v_readlane_b32 s22, v254, 35
	v_readlane_b32 s23, v254, 36
	v_readlane_b32 s25, v254, 38
	v_readlane_b32 s26, v254, 39
	v_readlane_b32 s27, v254, 40
	v_readlane_b32 s28, v254, 41
	v_readlane_b32 s29, v254, 42
	v_readlane_b32 s30, v254, 43
	v_readlane_b32 s31, v254, 44
	v_readlane_b32 s19, v254, 11
	s_add_u32 s38, s16, s34
	s_addc_u32 s39, s17, s35
	s_add_u32 s36, s6, s34
	s_addc_u32 s37, s7, s35
	v_lshlrev_b32_e32 v142, 13, v62
	v_lshl_add_u32 v142, v34, 2, v142
	s_waitcnt vmcnt(0)
; DI u16 f2bf(float x) { u32 u = __float_as_uint(x); u += 0x7fffu + ((u >> 16) & 1u); return (u16)(u >> 16); }
; DI float bf2f(u16 v) { return __uint_as_float(((u32)v) << 16); }
; DI void hyena_item_lat(const Params& p, int l, int it) {
;     ...
;   float ssq = 0.f;
;   for (int t = 0; t < 32; ++t) ssq += WSP(const float, OFF_PART)[(size_t)(f * 32 + t) * 256 + c];
;   const float scale = rsqrtf(ssq + EPSF);
;   const float bias = p.in[I_HYBIAS][l * 256 + c];
;   const u16* X1C = WSP(const u16, OFF_X1C);
;   u16* YM = WSP(u16, OFF_ACT);
;   const int b = l16;
; #pragma unroll
;   for (int i = 0; i < 8; ++i)
; #pragma unroll
;     for (int r = 0; r < 4; ++r) {
;       const int t = tt0 + 16 * i + kg * 4 + r;
;       const size_t row = (size_t)b * TPB + posoff + t;
;       const float uu = bf2f(UT[((size_t)(c * 16 + b)) * TPB + posoff + t]);
;       const float x1 = bf2f(X1C[row * 256 + c]);
;       YM[row * 1024 + c] = f2bf(x1 * (scale * acc[i][r] + bias * uu));
;     }
	v_add_f32_e32 v36, 0, v38
	v_add_f32_e32 v36, v36, v39
	v_add_f32_e32 v36, v36, v40
	v_add_f32_e32 v36, v36, v41
	v_add_f32_e32 v36, v36, v42
	v_add_f32_e32 v36, v36, v43
	v_add_f32_e32 v36, v36, v44
	v_add_f32_e32 v36, v36, v45
	v_add_f32_e32 v36, v36, v46
	v_add_f32_e32 v36, v36, v47
	v_add_f32_e32 v36, v36, v48
	v_add_f32_e32 v36, v36, v49
	v_add_f32_e32 v36, v36, v50
	v_add_f32_e32 v36, v36, v51
	v_add_f32_e32 v36, v36, v52
	v_add_f32_e32 v36, v36, v53
	v_add_f32_e32 v36, v36, v54
	v_add_f32_e32 v36, v36, v55
	v_add_f32_e32 v36, v36, v56
	v_add_f32_e32 v36, v36, v57
	v_add_f32_e32 v36, v36, v58
	v_add_f32_e32 v36, v36, v65
	v_add_f32_e32 v36, v36, v66
	v_add_f32_e32 v36, v36, v67
	v_add_f32_e32 v36, v36, v68
	v_add_f32_e32 v36, v36, v69
	v_add_f32_e32 v36, v36, v70
	v_add_f32_e32 v36, v36, v71
	v_add_f32_e32 v36, v36, v72
	v_add_f32_e32 v36, v36, v73
	v_add_f32_e32 v36, v36, v74
	v_add_f32_e32 v36, v36, v75
	s_mov_b32 s13, 0x800000
	v_add_f32_e32 v36, 0x358637bd, v36
	v_cmp_gt_f32_e32 vcc, s13, v36
	v_mul_f32_e32 v35, 0x4b800000, v36
	s_movk_i32 s13, 0x900
	s_nop 0
	v_cndmask_b32_e32 v36, v36, v35, vcc
	v_rsq_f32_e32 v36, v36
	s_nop 0
	v_mul_f32_e32 v35, 0x45800000, v36
	v_cndmask_b32_e32 v36, v36, v35, vcc
	v_lshlrev_b32_e32 v92, 16, v76
	v_mul_f32_e32 v92, v37, v92
	v_fmac_f32_e32 v92, v28, v36
	v_mov_b32_e32 v28, v92
	v_and_b32_e32 v92, 0xffff0000, v76
	v_mul_f32_e32 v92, v37, v92
	v_fmac_f32_e32 v92, v29, v36
	v_mov_b32_e32 v29, v92
	v_lshlrev_b32_e32 v92, 16, v77
	v_mul_f32_e32 v92, v37, v92
	v_fmac_f32_e32 v92, v30, v36
	v_mov_b32_e32 v30, v92
	v_and_b32_e32 v92, 0xffff0000, v77
	v_mul_f32_e32 v92, v37, v92
	v_fmac_f32_e32 v92, v31, v36
	v_mov_b32_e32 v31, v92
	v_lshlrev_b32_e32 v92, 16, v78
	v_mul_f32_e32 v92, v37, v92
	v_fmac_f32_e32 v92, v24, v36
	v_mov_b32_e32 v24, v92
	v_and_b32_e32 v92, 0xffff0000, v78
	v_mul_f32_e32 v92, v37, v92
	v_fmac_f32_e32 v92, v25, v36
	v_mov_b32_e32 v25, v92
	v_lshlrev_b32_e32 v92, 16, v79
	v_mul_f32_e32 v92, v37, v92
	v_fmac_f32_e32 v92, v26, v36
	v_mov_b32_e32 v26, v92
	v_and_b32_e32 v92, 0xffff0000, v79
	v_mul_f32_e32 v92, v37, v92
	v_fmac_f32_e32 v92, v27, v36
	v_mov_b32_e32 v27, v92
	v_lshlrev_b32_e32 v92, 16, v80
	v_mul_f32_e32 v92, v37, v92
	v_fmac_f32_e32 v92, v20, v36
	v_mov_b32_e32 v20, v92
	v_and_b32_e32 v92, 0xffff0000, v80
	v_mul_f32_e32 v92, v37, v92
	v_fmac_f32_e32 v92, v21, v36
	v_mov_b32_e32 v21, v92
	v_lshlrev_b32_e32 v92, 16, v81
	v_mul_f32_e32 v92, v37, v92
	v_fmac_f32_e32 v92, v22, v36
	v_mov_b32_e32 v22, v92
	v_and_b32_e32 v92, 0xffff0000, v81
	v_mul_f32_e32 v92, v37, v92
	v_fmac_f32_e32 v92, v23, v36
	v_mov_b32_e32 v23, v92
	v_lshlrev_b32_e32 v92, 16, v82
	v_mul_f32_e32 v92, v37, v92
	v_fmac_f32_e32 v92, v16, v36
	v_mov_b32_e32 v16, v92
	v_and_b32_e32 v92, 0xffff0000, v82
	v_mul_f32_e32 v92, v37, v92
	v_fmac_f32_e32 v92, v17, v36
	v_mov_b32_e32 v17, v92
	v_lshlrev_b32_e32 v92, 16, v83
	v_mul_f32_e32 v92, v37, v92
	v_fmac_f32_e32 v92, v18, v36
	v_mov_b32_e32 v18, v92
	v_and_b32_e32 v92, 0xffff0000, v83
	v_mul_f32_e32 v92, v37, v92
	v_fmac_f32_e32 v92, v19, v36
	v_mov_b32_e32 v19, v92
	v_lshlrev_b32_e32 v92, 16, v84
	v_mul_f32_e32 v92, v37, v92
	v_fmac_f32_e32 v92, v12, v36
	v_mov_b32_e32 v12, v92
	v_and_b32_e32 v92, 0xffff0000, v84
	v_mul_f32_e32 v92, v37, v92
	v_fmac_f32_e32 v92, v13, v36
	v_mov_b32_e32 v13, v92
	v_lshlrev_b32_e32 v92, 16, v85
	v_mul_f32_e32 v92, v37, v92
	v_fmac_f32_e32 v92, v14, v36
	v_mov_b32_e32 v14, v92
	v_and_b32_e32 v92, 0xffff0000, v85
	v_mul_f32_e32 v92, v37, v92
	v_fmac_f32_e32 v92, v15, v36
	v_mov_b32_e32 v15, v92
	v_lshlrev_b32_e32 v92, 16, v86
	v_mul_f32_e32 v92, v37, v92
	v_fmac_f32_e32 v92, v8, v36
	v_mov_b32_e32 v8, v92
	v_and_b32_e32 v92, 0xffff0000, v86
	v_mul_f32_e32 v92, v37, v92
	v_fmac_f32_e32 v92, v9, v36
	v_mov_b32_e32 v9, v92
	v_lshlrev_b32_e32 v92, 16, v87
	v_mul_f32_e32 v92, v37, v92
	v_fmac_f32_e32 v92, v10, v36
	v_mov_b32_e32 v10, v92
	v_and_b32_e32 v92, 0xffff0000, v87
	v_mul_f32_e32 v92, v37, v92
	v_fmac_f32_e32 v92, v11, v36
	v_mov_b32_e32 v11, v92
	v_lshlrev_b32_e32 v92, 16, v88
	v_mul_f32_e32 v92, v37, v92
	v_fmac_f32_e32 v92, v4, v36
	v_mov_b32_e32 v4, v92
	v_and_b32_e32 v92, 0xffff0000, v88
	v_mul_f32_e32 v92, v37, v92
	v_fmac_f32_e32 v92, v5, v36
	v_mov_b32_e32 v5, v92
	v_lshlrev_b32_e32 v92, 16, v89
	v_mul_f32_e32 v92, v37, v92
	v_fmac_f32_e32 v92, v6, v36
	v_mov_b32_e32 v6, v92
	v_and_b32_e32 v92, 0xffff0000, v89
	v_mul_f32_e32 v92, v37, v92
	v_fmac_f32_e32 v92, v7, v36
	v_mov_b32_e32 v7, v92
	v_lshlrev_b32_e32 v92, 16, v90
	v_mul_f32_e32 v92, v37, v92
	v_fmac_f32_e32 v92, v0, v36
	v_mov_b32_e32 v0, v92
	v_and_b32_e32 v92, 0xffff0000, v90
	v_mul_f32_e32 v92, v37, v92
	v_fmac_f32_e32 v92, v1, v36
	v_mov_b32_e32 v1, v92
	v_lshlrev_b32_e32 v92, 16, v91
	v_mul_f32_e32 v92, v37, v92
	v_fmac_f32_e32 v92, v2, v36
	v_mov_b32_e32 v2, v92
	v_and_b32_e32 v92, 0xffff0000, v91
	v_mul_f32_e32 v92, v37, v92
	v_fmac_f32_e32 v92, v3, v36
	v_mov_b32_e32 v3, v92
	s_lshl_b32 s38, s34, 16
	s_add_u32 s38, s96, s38
	s_addc_u32 s39, s97, 0
	global_store_dwordx4 v142, v[28:31], s[38:39]
	global_store_dwordx4 v142, v[24:27], s[38:39] offset:64
	global_store_dwordx4 v142, v[20:23], s[38:39] offset:128
	global_store_dwordx4 v142, v[16:19], s[38:39] offset:192
	global_store_dwordx4 v142, v[12:15], s[38:39] offset:256
	global_store_dwordx4 v142, v[8:11], s[38:39] offset:320
	global_store_dwordx4 v142, v[4:7], s[38:39] offset:384
	global_store_dwordx4 v142, v[0:3], s[38:39] offset:448
